# attention / xattn per-step xor-32 max exchange: ds_bpermute replaced by v_permlane32_swap
# baseline (speedup 1.0000x reference)
; #define MFMA(a, b, c) __builtin_amdgcn_mfma_f32_32x32x16_bf16((a), (b), (c), 0, 0, 0)
; DI unsigned pack2(float a, float b) { const f32x2 v = {a, b}; return __builtin_bit_cast(unsigned, __builtin_convertvector(v, bf16v2)); }
; DI void attn_item(const Params& p, char* lds, int item) {
;     ...
;       mx = fmaxf(mx, __shfl_xor(mx, 32));
;       const float mnew = fmaxf(mrun, mx);
;       const float alpha = __builtin_amdgcn_exp2f(mrun - mnew);
;       mrun = mnew;
;       float ps = 0.f;
; #pragma unroll
;       for (int sub = 0; sub < 2; ++sub)
; #pragma unroll
;         for (int r = 0; r < 16; ++r) { const float e = __builtin_amdgcn_exp2f(S[sub][r] - mnew); S[sub][r] = e; ps += e; }
;       lrun = lrun * alpha + ps;
; #pragma unroll
;       for (int r = 0; r < 16; ++r) { O[0][r] *= alpha; O[1][r] *= alpha; }
; #pragma unroll
;       for (int sub = 0; sub < 2; ++sub) {
;         bf16x8 Pf[2];
; #pragma unroll
;         for (int ks = 0; ks < 2; ++ks) {
;           union { bf16x8 v; unsigned u[4]; } cv;
;           for (int j2 = 0; j2 < 4; ++j2) cv.u[j2] = pack2(S[sub][8 * ks + 2 * j2], S[sub][8 * ks + 2 * j2 + 1]);
;           Pf[ks] = cv.v;
;         }
;         const u16* vl = Vl + cur * 64 * 72 + l31 * 72 + sub * 32 + 8 * hh;
; #pragma unroll
;         for (int dt = 0; dt < 2; ++dt)
; #pragma unroll
;           for (int ks = 0; ks < 2; ++ks) O[dt] = MFMA(ldfrag(vl + dt * 32 * 72 + 16 * ks), Pf[ks], O[dt]);
;       }
.LBB0_372:
	s_or_b64 exec, exec, s[16:17]
	s_nop 5
	v_mov_b32_e32 v48, v0
	s_nop 1
	v_permlane32_swap_b32_e32 v48, v0
	s_nop 0
	s_waitcnt lgkmcnt(0)
	v_max3_f32 v48, v138, v0, v48
	v_sub_f32_e32 v49, v92, v48
	v_exp_f32_e32 v49, v49
	v_sub_f32_e32 v51, v93, v48
	v_exp_f32_e32 v51, v51
	v_sub_f32_e32 v52, v88, v48
	v_exp_f32_e32 v52, v52
	v_sub_f32_e32 v53, v89, v48
	v_exp_f32_e32 v53, v53
	v_sub_f32_e32 v12, v12, v48
	v_add_f32_e32 v50, 0, v49
	v_exp_f32_e32 v54, v12
	v_add_f32_e32 v50, v51, v50
	v_add_f32_e32 v50, v52, v50
	v_add_f32_e32 v50, v53, v50
	v_sub_f32_e32 v13, v13, v48
	v_add_f32_e32 v12, v54, v50
	v_exp_f32_e32 v50, v13
	v_sub_f32_e32 v10, v10, v48
	v_exp_f32_e32 v55, v10
	v_sub_f32_e32 v11, v11, v48
	v_add_f32_e32 v12, v50, v12
	v_exp_f32_e32 v11, v11
	v_add_f32_e32 v10, v55, v12
	v_sub_f32_e32 v12, v96, v48
	v_exp_f32_e32 v56, v12
	v_sub_f32_e32 v12, v97, v48
	v_exp_f32_e32 v57, v12
	v_sub_f32_e32 v12, v94, v48
	v_exp_f32_e32 v58, v12
	v_sub_f32_e32 v12, v95, v48
	v_exp_f32_e32 v59, v12
	v_sub_f32_e32 v12, v90, v48
	v_exp_f32_e32 v60, v12
	v_sub_f32_e32 v12, v91, v48
	v_exp_f32_e32 v61, v12
	v_sub_f32_e32 v12, v14, v48
	v_exp_f32_e32 v62, v12
	v_sub_f32_e32 v12, v15, v48
	v_exp_f32_e32 v63, v12
	v_sub_f32_e32 v12, v98, v48
	v_exp_f32_e32 v88, v12
	v_sub_f32_e32 v12, v99, v48
	v_exp_f32_e32 v89, v12
	v_sub_f32_e32 v12, v100, v48
	v_exp_f32_e32 v90, v12
	v_sub_f32_e32 v12, v101, v48
	v_exp_f32_e32 v91, v12
	v_sub_f32_e32 v12, v102, v48
	v_exp_f32_e32 v92, v12
	v_sub_f32_e32 v12, v103, v48
	v_exp_f32_e32 v93, v12
	v_sub_f32_e32 v12, v104, v48
	v_exp_f32_e32 v94, v12
	v_sub_f32_e32 v12, v105, v48
	v_exp_f32_e32 v95, v12
	v_sub_f32_e32 v12, v106, v48
	v_exp_f32_e32 v96, v12
	v_sub_f32_e32 v12, v107, v48
	v_add_f32_e32 v10, v11, v10
	v_exp_f32_e32 v97, v12
	v_sub_f32_e32 v12, v108, v48
	v_add_f32_e32 v10, v56, v10
	v_exp_f32_e32 v98, v12
	v_sub_f32_e32 v12, v109, v48
	v_add_f32_e32 v10, v57, v10
	v_exp_f32_e32 v99, v12
	v_sub_f32_e32 v12, v110, v48
	v_add_f32_e32 v10, v58, v10
	v_exp_f32_e32 v100, v12
	v_sub_f32_e32 v12, v111, v48
	v_sub_f32_e32 v0, v138, v48
	v_add_f32_e32 v10, v59, v10
	v_exp_f32_e32 v101, v12
	v_sub_f32_e32 v12, v112, v48
	v_add_f32_e32 v10, v60, v10
	v_exp_f32_e32 v102, v12
	v_sub_f32_e32 v12, v113, v48
	v_exp_f32_e32 v0, v0
	v_add_u32_e32 v104, s30, v133
	v_add_f32_e32 v10, v61, v10
	v_exp_f32_e32 v103, v12
	v_cvt_pk_bf16_f32 v12, v49, v51
	v_cvt_pk_bf16_f32 v13, v52, v53
	v_cvt_pk_bf16_f32 v14, v54, v50
	v_cvt_pk_bf16_f32 v15, v55, v11
	v_cvt_pk_bf16_f32 v50, v56, v57
	v_cvt_pk_bf16_f32 v51, v58, v59
	v_cvt_pk_bf16_f32 v52, v60, v61
	ds_read_b128 v[54:57], v104 offset:18432
	ds_read_b128 v[58:61], v104 offset:18464
	v_pk_mul_f32 v[46:47], v[46:47], v[0:1] op_sel_hi:[1,0]
	v_pk_mul_f32 v[44:45], v[44:45], v[0:1] op_sel_hi:[1,0]
	v_pk_mul_f32 v[42:43], v[42:43], v[0:1] op_sel_hi:[1,0]
	v_pk_mul_f32 v[40:41], v[40:41], v[0:1] op_sel_hi:[1,0]
	v_pk_mul_f32 v[38:39], v[38:39], v[0:1] op_sel_hi:[1,0]
	v_pk_mul_f32 v[36:37], v[36:37], v[0:1] op_sel_hi:[1,0]
	v_pk_mul_f32 v[34:35], v[34:35], v[0:1] op_sel_hi:[1,0]
	v_pk_mul_f32 v[32:33], v[32:33], v[0:1] op_sel_hi:[1,0]
	v_pk_mul_f32 v[30:31], v[30:31], v[0:1] op_sel_hi:[1,0]
	v_pk_mul_f32 v[28:29], v[28:29], v[0:1] op_sel_hi:[1,0]
	s_waitcnt lgkmcnt(1)
	v_mfma_f32_32x32x16_bf16 v[32:47], v[54:57], v[12:15], v[32:47]
	ds_read_b128 v[54:57], v104 offset:23040
	v_mul_f32_e64 v26, v26, v0
	v_mul_f32_e64 v27, v27, v0
	v_mul_f32_e64 v24, v24, v0
	v_mul_f32_e64 v25, v25, v0
	v_pk_mul_f32 v[22:23], v[22:23], v[0:1] op_sel_hi:[1,0]
	v_pk_mul_f32 v[20:21], v[20:21], v[0:1] op_sel_hi:[1,0]
	v_pk_mul_f32 v[18:19], v[18:19], v[0:1] op_sel_hi:[1,0]
	v_pk_mul_f32 v[16:17], v[16:17], v[0:1] op_sel_hi:[1,0]
	v_cvt_pk_bf16_f32 v53, v62, v63
	v_add_f32_e32 v10, v62, v10
	s_waitcnt lgkmcnt(0)
	v_mfma_f32_32x32x16_bf16 v[16:31], v[54:57], v[12:15], v[16:31]
	ds_read_b128 v[12:15], v104 offset:23072
	ds_read_b128 v[54:57], v104 offset:18496
	v_add_f32_e32 v10, v63, v10
	v_add_f32_e32 v10, v88, v10
	v_add_f32_e32 v10, v89, v10
	v_add_f32_e32 v10, v90, v10
	v_add_f32_e32 v10, v91, v10
	v_mfma_f32_32x32x16_bf16 v[32:47], v[58:61], v[50:53], v[32:47]
	v_add_f32_e32 v10, v92, v10
	v_add_f32_e32 v10, v93, v10
	v_add_f32_e32 v10, v94, v10
	v_add_f32_e32 v10, v95, v10
	v_add_f32_e32 v10, v96, v10
	v_add_f32_e32 v10, v97, v10
	v_add_f32_e32 v10, v98, v10
	s_waitcnt lgkmcnt(1)
	v_mfma_f32_32x32x16_bf16 v[16:31], v[12:15], v[50:53], v[16:31]
	v_cvt_pk_bf16_f32 v12, v88, v89
	v_cvt_pk_bf16_f32 v13, v90, v91
	v_cvt_pk_bf16_f32 v14, v92, v93
	v_cvt_pk_bf16_f32 v15, v94, v95
	v_cvt_pk_bf16_f32 v50, v96, v97
	v_cvt_pk_bf16_f32 v51, v98, v99
	v_cvt_pk_bf16_f32 v52, v100, v101
	s_waitcnt lgkmcnt(0)
	v_mfma_f32_32x32x16_bf16 v[32:47], v[54:57], v[12:15], v[32:47]
	ds_read_b128 v[54:57], v104 offset:18528
	v_cvt_pk_bf16_f32 v53, v102, v103
	v_add_f32_e32 v10, v99, v10
	v_add_f32_e32 v10, v100, v10
	v_add_f32_e32 v10, v101, v10
	v_add_f32_e32 v10, v102, v10
	v_add_f32_e32 v10, v103, v10
	s_waitcnt lgkmcnt(0)
	v_mfma_f32_32x32x16_bf16 v[32:47], v[54:57], v[50:53], v[32:47]
	ds_read_b128 v[54:57], v104 offset:23104
	v_fmac_f32_e32 v10, v137, v0
	v_mov_b32_e32 v138, v48
	v_mov_b32_e32 v137, v10
	s_waitcnt lgkmcnt(0)
	v_mfma_f32_32x32x16_bf16 v[16:31], v[54:57], v[12:15], v[16:31]
	ds_read_b128 v[12:15], v104 offset:23136
	s_waitcnt lgkmcnt(0)
	v_mfma_f32_32x32x16_bf16 v[16:31], v[12:15], v[50:53], v[16:31]

; #define MFMA(a, b, c) __builtin_amdgcn_mfma_f32_32x32x16_bf16((a), (b), (c), 0, 0, 0)
; DI unsigned pack2(float a, float b) { const f32x2 v = {a, b}; return __builtin_bit_cast(unsigned, __builtin_convertvector(v, bf16v2)); }
; DI void attn_item(const Params& p, char* lds, int item) {
;     ...
;       mx = fmaxf(mx, __shfl_xor(mx, 32));
;       const float mnew = fmaxf(mrun, mx);
;       const float alpha = __builtin_amdgcn_exp2f(mrun - mnew);
;       mrun = mnew;
;       float ps = 0.f;
; #pragma unroll
;       for (int sub = 0; sub < 2; ++sub)
; #pragma unroll
;         for (int r = 0; r < 16; ++r) { const float e = __builtin_amdgcn_exp2f(S[sub][r] - mnew); S[sub][r] = e; ps += e; }
;       lrun = lrun * alpha + ps;
; #pragma unroll
;       for (int r = 0; r < 16; ++r) { O[0][r] *= alpha; O[1][r] *= alpha; }
; #pragma unroll
;       for (int sub = 0; sub < 2; ++sub) {
;         bf16x8 Pf[2];
; #pragma unroll
;         for (int ks = 0; ks < 2; ++ks) {
;           union { bf16x8 v; unsigned u[4]; } cv;
;           for (int j2 = 0; j2 < 4; ++j2) cv.u[j2] = pack2(S[sub][8 * ks + 2 * j2], S[sub][8 * ks + 2 * j2 + 1]);
;           Pf[ks] = cv.v;
;         }
;         const u16* vl = Vl + cur * 64 * 72 + l31 * 72 + sub * 32 + 8 * hh;
; #pragma unroll
;         for (int dt = 0; dt < 2; ++dt)
; #pragma unroll
;           for (int ks = 0; ks < 2; ++ks) O[dt] = MFMA(ldfrag(vl + dt * 32 * 72 + 16 * ks), Pf[ks], O[dt]);
;       }
.LBB0_406:
	s_or_b64 exec, exec, s[16:17]
	s_nop 5
	v_mov_b32_e32 v48, v0
	s_nop 1
	v_permlane32_swap_b32_e32 v48, v0
	s_nop 0
	s_waitcnt lgkmcnt(0)
	v_max3_f32 v48, v138, v0, v48
	v_sub_f32_e32 v49, v92, v48
	v_exp_f32_e32 v49, v49
	v_sub_f32_e32 v51, v93, v48
	v_exp_f32_e32 v51, v51
	v_sub_f32_e32 v52, v88, v48
	v_exp_f32_e32 v52, v52
	v_sub_f32_e32 v53, v89, v48
	v_exp_f32_e32 v53, v53
	v_sub_f32_e32 v12, v12, v48
	v_add_f32_e32 v50, 0, v49
	v_exp_f32_e32 v54, v12
	v_add_f32_e32 v50, v51, v50
	v_add_f32_e32 v50, v52, v50
	v_add_f32_e32 v50, v53, v50
	v_sub_f32_e32 v13, v13, v48
	v_add_f32_e32 v12, v54, v50
	v_exp_f32_e32 v50, v13
	v_sub_f32_e32 v10, v10, v48
	v_exp_f32_e32 v55, v10
	v_sub_f32_e32 v11, v11, v48
	v_add_f32_e32 v12, v50, v12
	v_exp_f32_e32 v11, v11
	v_add_f32_e32 v10, v55, v12
	v_sub_f32_e32 v12, v96, v48
	v_exp_f32_e32 v56, v12
	v_sub_f32_e32 v12, v97, v48
	v_exp_f32_e32 v57, v12
	v_sub_f32_e32 v12, v94, v48
	v_exp_f32_e32 v58, v12
	v_sub_f32_e32 v12, v95, v48
	v_exp_f32_e32 v59, v12
	v_sub_f32_e32 v12, v90, v48
	v_exp_f32_e32 v60, v12
	v_sub_f32_e32 v12, v91, v48
	v_exp_f32_e32 v61, v12
	v_sub_f32_e32 v12, v14, v48
	v_exp_f32_e32 v62, v12
	v_sub_f32_e32 v12, v15, v48
	v_exp_f32_e32 v63, v12
	v_sub_f32_e32 v12, v98, v48
	v_exp_f32_e32 v88, v12
	v_sub_f32_e32 v12, v99, v48
	v_exp_f32_e32 v89, v12
	v_sub_f32_e32 v12, v100, v48
	v_exp_f32_e32 v90, v12
	v_sub_f32_e32 v12, v101, v48
	v_exp_f32_e32 v91, v12
	v_sub_f32_e32 v12, v102, v48
	v_exp_f32_e32 v92, v12
	v_sub_f32_e32 v12, v103, v48
	v_exp_f32_e32 v93, v12
	v_sub_f32_e32 v12, v104, v48
	v_exp_f32_e32 v94, v12
	v_sub_f32_e32 v12, v105, v48
	v_exp_f32_e32 v95, v12
	v_sub_f32_e32 v12, v106, v48
	v_exp_f32_e32 v96, v12
	v_sub_f32_e32 v12, v107, v48
	v_add_f32_e32 v10, v11, v10
	v_exp_f32_e32 v97, v12
	v_sub_f32_e32 v12, v108, v48
	v_add_f32_e32 v10, v56, v10
	v_exp_f32_e32 v98, v12
	v_sub_f32_e32 v12, v109, v48
	v_add_f32_e32 v10, v57, v10
	v_exp_f32_e32 v99, v12
	v_sub_f32_e32 v12, v110, v48
	v_add_f32_e32 v10, v58, v10
	v_exp_f32_e32 v100, v12
	v_sub_f32_e32 v12, v111, v48
	v_sub_f32_e32 v0, v138, v48
	v_add_f32_e32 v10, v59, v10
	v_exp_f32_e32 v101, v12
	v_sub_f32_e32 v12, v112, v48
	v_add_f32_e32 v10, v60, v10
	v_exp_f32_e32 v102, v12
	v_sub_f32_e32 v12, v113, v48
	v_exp_f32_e32 v0, v0
	v_add_u32_e32 v104, s77, v133
	v_add_f32_e32 v10, v61, v10
	v_exp_f32_e32 v103, v12
	v_cvt_pk_bf16_f32 v12, v49, v51
	v_cvt_pk_bf16_f32 v13, v52, v53
	v_cvt_pk_bf16_f32 v14, v54, v50
	v_cvt_pk_bf16_f32 v15, v55, v11
	v_cvt_pk_bf16_f32 v50, v56, v57
	v_cvt_pk_bf16_f32 v51, v58, v59
	v_cvt_pk_bf16_f32 v52, v60, v61
	ds_read_b128 v[54:57], v104 offset:18432
	ds_read_b128 v[58:61], v104 offset:18464
	v_pk_mul_f32 v[46:47], v[46:47], v[0:1] op_sel_hi:[1,0]
	v_pk_mul_f32 v[44:45], v[44:45], v[0:1] op_sel_hi:[1,0]
	v_pk_mul_f32 v[42:43], v[42:43], v[0:1] op_sel_hi:[1,0]
	v_pk_mul_f32 v[40:41], v[40:41], v[0:1] op_sel_hi:[1,0]
	v_pk_mul_f32 v[38:39], v[38:39], v[0:1] op_sel_hi:[1,0]
	v_pk_mul_f32 v[36:37], v[36:37], v[0:1] op_sel_hi:[1,0]
	v_pk_mul_f32 v[34:35], v[34:35], v[0:1] op_sel_hi:[1,0]
	v_pk_mul_f32 v[32:33], v[32:33], v[0:1] op_sel_hi:[1,0]
	v_pk_mul_f32 v[30:31], v[30:31], v[0:1] op_sel_hi:[1,0]
	v_pk_mul_f32 v[28:29], v[28:29], v[0:1] op_sel_hi:[1,0]
	s_waitcnt lgkmcnt(1)
	v_mfma_f32_32x32x16_bf16 v[32:47], v[54:57], v[12:15], v[32:47]
	ds_read_b128 v[54:57], v104 offset:23040
	v_mul_f32_e64 v26, v26, v0
	v_mul_f32_e64 v27, v27, v0
	v_mul_f32_e64 v24, v24, v0
	v_mul_f32_e64 v25, v25, v0
	v_pk_mul_f32 v[22:23], v[22:23], v[0:1] op_sel_hi:[1,0]
	v_pk_mul_f32 v[20:21], v[20:21], v[0:1] op_sel_hi:[1,0]
	v_pk_mul_f32 v[18:19], v[18:19], v[0:1] op_sel_hi:[1,0]
	v_pk_mul_f32 v[16:17], v[16:17], v[0:1] op_sel_hi:[1,0]
	v_cvt_pk_bf16_f32 v53, v62, v63
	v_add_f32_e32 v10, v62, v10
	s_waitcnt lgkmcnt(0)
	v_mfma_f32_32x32x16_bf16 v[16:31], v[54:57], v[12:15], v[16:31]
	ds_read_b128 v[12:15], v104 offset:23072
	ds_read_b128 v[54:57], v104 offset:18496
	v_add_f32_e32 v10, v63, v10
	v_add_f32_e32 v10, v88, v10
	v_add_f32_e32 v10, v89, v10
	v_add_f32_e32 v10, v90, v10
	v_add_f32_e32 v10, v91, v10
	v_mfma_f32_32x32x16_bf16 v[32:47], v[58:61], v[50:53], v[32:47]
	v_add_f32_e32 v10, v92, v10
	v_add_f32_e32 v10, v93, v10
	v_add_f32_e32 v10, v94, v10
	v_add_f32_e32 v10, v95, v10
	v_add_f32_e32 v10, v96, v10
	v_add_f32_e32 v10, v97, v10
	v_add_f32_e32 v10, v98, v10
	s_waitcnt lgkmcnt(1)
	v_mfma_f32_32x32x16_bf16 v[16:31], v[12:15], v[50:53], v[16:31]
	v_cvt_pk_bf16_f32 v12, v88, v89
	v_cvt_pk_bf16_f32 v13, v90, v91
	v_cvt_pk_bf16_f32 v14, v92, v93
	v_cvt_pk_bf16_f32 v15, v94, v95
	v_cvt_pk_bf16_f32 v50, v96, v97
	v_cvt_pk_bf16_f32 v51, v98, v99
	v_cvt_pk_bf16_f32 v52, v100, v101
	s_waitcnt lgkmcnt(0)
	v_mfma_f32_32x32x16_bf16 v[32:47], v[54:57], v[12:15], v[32:47]
	ds_read_b128 v[54:57], v104 offset:18528
	v_cvt_pk_bf16_f32 v53, v102, v103
	v_add_f32_e32 v10, v99, v10
	v_add_f32_e32 v10, v100, v10
	v_add_f32_e32 v10, v101, v10
	v_add_f32_e32 v10, v102, v10
	v_add_f32_e32 v10, v103, v10
	s_waitcnt lgkmcnt(0)
	v_mfma_f32_32x32x16_bf16 v[32:47], v[54:57], v[50:53], v[32:47]
	ds_read_b128 v[54:57], v104 offset:23104
	v_fmac_f32_e32 v10, v137, v0
	v_mov_b32_e32 v138, v48
	v_mov_b32_e32 v137, v10
	s_waitcnt lgkmcnt(0)
	v_mfma_f32_32x32x16_bf16 v[16:31], v[54:57], v[12:15], v[16:31]
	ds_read_b128 v[12:15], v104 offset:23136
	s_waitcnt lgkmcnt(0)
	v_mfma_f32_32x32x16_bf16 v[16:31], v[12:15], v[50:53], v[16:31]

; #define MFMA(a, b, c) __builtin_amdgcn_mfma_f32_32x32x16_bf16((a), (b), (c), 0, 0, 0)
; DI unsigned pack2(float a, float b) { const f32x2 v = {a, b}; return __builtin_bit_cast(unsigned, __builtin_convertvector(v, bf16v2)); }
; DI f32x16 zero16() { f32x16 z; for (int i = 0; i < 16; ++i) z[i] = 0.f; return z; }
; DI void phase_xattn(const Params& p, char* lds) {
;     ...
;       const u16* kl = Kl + cur * 32 * 264 + pi * 264 + 8 * hh;
;       const u16* vl = Vl + cur * 128 * 40 + l31 * 40 + 8 * hh;
;       f32x16 S = zero16();
; #pragma unroll
;       for (int kk = 0; kk < 16; ++kk) S = MFMA(ldfrag(kl + kk * 16), Qf[kk], S);
;       float mx = -INFINITY;
; #pragma unroll
;       for (int r = 0; r < 16; ++r) { S[r] *= 0.09016844005556021f; mx = fmaxf(mx, S[r]); }
;       mx = fmaxf(mx, __shfl_xor(mx, 32));
;       const float mnew = fmaxf(mrun, mx), alpha = __builtin_amdgcn_exp2f(mrun - mnew);
;       mrun = mnew;
;       float ps = 0.f;
; #pragma unroll
;       for (int r = 0; r < 16; ++r) { const float e = __builtin_amdgcn_exp2f(S[r] - mnew); S[r] = e; ps += e; }
;       lrun = lrun * alpha + ps;
;       bf16x8 Pf[2];
; #pragma unroll
;       for (int ks = 0; ks < 2; ++ks) {
;         union { bf16x8 v; unsigned u[4]; } cv;
;         for (int j2 = 0; j2 < 4; ++j2) cv.u[j2] = pack2(S[8 * ks + 2 * j2], S[8 * ks + 2 * j2 + 1]);
;         Pf[ks] = cv.v;
;       }
; #pragma unroll
;       for (int dt = 0; dt < 4; ++dt) {
; #pragma unroll
;         for (int r = 0; r < 16; ++r) O[dt][r] *= alpha;
; #pragma unroll
;         for (int ks = 0; ks < 2; ++ks) O[dt] = MFMA(ldfrag(vl + dt * 32 * 40 + 16 * ks), Pf[ks], O[dt]);
.LBB0_905:
	s_and_b32 s17, s16, 1
	s_mul_i32 s6, s17, 0x4200
	v_add_u32_e32 v187, s6, v182
	ds_read_b128 v[64:67], v187
	ds_read_b128 v[188:191], v187 offset:32
	s_mul_i32 s6, s17, 0x2800
	v_add_u32_e32 v200, s6, v183
	s_and_b32 s6, s16, 7
	s_waitcnt vmcnt(15) lgkmcnt(1)
	v_mfma_f32_32x32x16_bf16 v[64:79], v[64:67], v[92:95], 0
	s_cmp_lg_u32 s6, 7
	s_waitcnt vmcnt(14) lgkmcnt(0)
	v_mfma_f32_32x32x16_bf16 v[64:79], v[188:191], v[96:99], v[64:79]
	ds_read_b128 v[188:191], v187 offset:64
	ds_read_b128 v[192:195], v187 offset:96
	s_waitcnt vmcnt(13) lgkmcnt(1)
	v_mfma_f32_32x32x16_bf16 v[64:79], v[188:191], v[100:103], v[64:79]
	s_waitcnt vmcnt(12) lgkmcnt(0)
	v_mfma_f32_32x32x16_bf16 v[64:79], v[192:195], v[104:107], v[64:79]
	ds_read_b128 v[188:191], v187 offset:128
	ds_read_b128 v[192:195], v187 offset:160
	s_waitcnt vmcnt(11) lgkmcnt(1)
	v_mfma_f32_32x32x16_bf16 v[64:79], v[188:191], v[108:111], v[64:79]
	s_waitcnt vmcnt(10) lgkmcnt(0)
	v_mfma_f32_32x32x16_bf16 v[64:79], v[192:195], v[112:115], v[64:79]
	ds_read_b128 v[188:191], v187 offset:192
	ds_read_b128 v[192:195], v187 offset:224
	s_waitcnt vmcnt(9) lgkmcnt(1)
	v_mfma_f32_32x32x16_bf16 v[64:79], v[188:191], v[116:119], v[64:79]
	s_waitcnt vmcnt(8) lgkmcnt(0)
	v_mfma_f32_32x32x16_bf16 v[64:79], v[192:195], v[120:123], v[64:79]
	ds_read_b128 v[188:191], v187 offset:256
	ds_read_b128 v[192:195], v187 offset:288
	s_waitcnt vmcnt(7) lgkmcnt(1)
	v_mfma_f32_32x32x16_bf16 v[64:79], v[188:191], v[124:127], v[64:79]
	s_waitcnt vmcnt(6) lgkmcnt(0)
	v_mfma_f32_32x32x16_bf16 v[64:79], v[192:195], v[128:131], v[64:79]
	ds_read_b128 v[188:191], v187 offset:320
	ds_read_b128 v[192:195], v187 offset:352
	s_waitcnt vmcnt(5) lgkmcnt(1)
	v_mfma_f32_32x32x16_bf16 v[64:79], v[188:191], v[132:135], v[64:79]
	s_waitcnt vmcnt(4) lgkmcnt(0)
	v_mfma_f32_32x32x16_bf16 v[64:79], v[192:195], v[136:139], v[64:79]
	ds_read_b128 v[188:191], v187 offset:384
	ds_read_b128 v[192:195], v187 offset:416
	s_waitcnt vmcnt(3) lgkmcnt(1)
	v_mfma_f32_32x32x16_bf16 v[64:79], v[188:191], v[140:143], v[64:79]
	s_waitcnt vmcnt(2) lgkmcnt(0)
	v_mfma_f32_32x32x16_bf16 v[64:79], v[192:195], v[144:147], v[64:79]
	ds_read_b128 v[188:191], v187 offset:448
	ds_read_b128 v[192:195], v187 offset:480
	s_waitcnt vmcnt(1) lgkmcnt(1)
	v_mfma_f32_32x32x16_bf16 v[64:79], v[188:191], v[148:151], v[64:79]
	ds_read_b128 v[188:191], v200 offset:33792
	ds_read_b128 v[196:199], v200 offset:33824
	s_waitcnt vmcnt(0) lgkmcnt(2)
	v_mfma_f32_32x32x16_bf16 v[64:79], v[192:195], v[152:155], v[64:79]
	s_nop 11
	v_mul_f32_e32 v187, 0x3db8aa3b, v64
	v_mul_f32_e32 v192, 0x3db8aa3b, v65
	v_mul_f32_e32 v193, 0x3db8aa3b, v66
	v_mul_f32_e32 v194, 0x3db8aa3b, v67
	v_max3_f32 v187, v187, s12, v192
	v_mul_f32_e32 v195, 0x3db8aa3b, v68
	v_mul_f32_e32 v201, 0x3db8aa3b, v69
	v_max3_f32 v187, v187, v193, v194
	v_mul_f32_e32 v202, 0x3db8aa3b, v70
	v_mul_f32_e32 v204, 0x3db8aa3b, v71
	v_max3_f32 v187, v187, v195, v201
	v_mul_f32_e32 v205, 0x3db8aa3b, v72
	v_mul_f32_e32 v206, 0x3db8aa3b, v73
	v_max3_f32 v187, v187, v202, v204
	v_mul_f32_e32 v207, 0x3db8aa3b, v74
	v_mul_f32_e32 v208, 0x3db8aa3b, v75
	v_max3_f32 v187, v187, v205, v206
	v_mul_f32_e32 v209, 0x3db8aa3b, v76
	v_mul_f32_e32 v210, 0x3db8aa3b, v77
	v_max3_f32 v187, v187, v207, v208
	v_mul_f32_e32 v211, 0x3db8aa3b, v78
	v_mul_f32_e32 v212, 0x3db8aa3b, v79
	v_max3_f32 v187, v187, v209, v210
	v_max3_f32 v187, v187, v211, v212
	v_mov_b32_e32 v201, v187
	s_nop 1
	v_permlane32_swap_b32_e32 v201, v187
	ds_read_b128 v[192:195], v200 offset:36352
	ds_read_b128 v[204:207], v200 offset:36384
	ds_read_b128 v[208:211], v200 offset:38912
	ds_read_b128 v[212:215], v200 offset:38944
	s_waitcnt lgkmcnt(4)
	v_max3_f32 v187, v186, v187, v201
	v_fma_f32 v64, v64, s2, -v187
	v_fma_f32 v65, v65, s2, -v187
	v_exp_f32_e32 v201, v64
	v_fma_f32 v66, v66, s2, -v187
	v_exp_f32_e32 v202, v65
	v_fma_f32 v67, v67, s2, -v187
	v_exp_f32_e32 v216, v66
	v_fma_f32 v68, v68, s2, -v187
	v_fma_f32 v76, v76, s2, -v187
	v_exp_f32_e32 v217, v67
	v_fma_f32 v69, v69, s2, -v187
	v_exp_f32_e32 v218, v68
	v_exp_f32_e32 v227, v76
	v_add_f32_e32 v76, 0, v201
	v_fma_f32 v70, v70, s2, -v187
	v_fma_f32 v72, v72, s2, -v187
	v_fma_f32 v73, v73, s2, -v187
	v_fma_f32 v74, v74, s2, -v187
	v_fma_f32 v75, v75, s2, -v187
	v_exp_f32_e32 v219, v69
	v_add_f32_e32 v76, v202, v76
	v_fma_f32 v71, v71, s2, -v187
	v_exp_f32_e32 v220, v70
	v_exp_f32_e32 v223, v72
	v_exp_f32_e32 v224, v73
	v_exp_f32_e32 v225, v74
	v_exp_f32_e32 v226, v75
	ds_read_b128 v[72:75], v200 offset:41472
	v_add_f32_e32 v76, v216, v76
	v_exp_f32_e32 v221, v71
	v_add_f32_e32 v76, v217, v76
	v_sub_f32_e32 v186, v186, v187
	v_add_f32_e32 v76, v218, v76
	v_exp_f32_e32 v186, v186
	v_add_f32_e32 v76, v219, v76
	v_add_f32_e32 v76, v220, v76
	v_add_f32_e32 v76, v221, v76
	v_add_f32_e32 v76, v223, v76
	v_fma_f32 v77, v77, s2, -v187
	v_fma_f32 v78, v78, s2, -v187
	v_fma_f32 v79, v79, s2, -v187
	v_cvt_pk_bf16_f32 v64, v201, v202
	v_cvt_pk_bf16_f32 v65, v216, v217
	v_cvt_pk_bf16_f32 v66, v218, v219
	v_cvt_pk_bf16_f32 v67, v220, v221
	v_pk_mul_f32 v[62:63], v[62:63], v[186:187] op_sel_hi:[1,0]
	v_pk_mul_f32 v[60:61], v[60:61], v[186:187] op_sel_hi:[1,0]
	v_pk_mul_f32 v[58:59], v[58:59], v[186:187] op_sel_hi:[1,0]
	v_pk_mul_f32 v[56:57], v[56:57], v[186:187] op_sel_hi:[1,0]
	v_pk_mul_f32 v[54:55], v[54:55], v[186:187] op_sel_hi:[1,0]
	v_pk_mul_f32 v[52:53], v[52:53], v[186:187] op_sel_hi:[1,0]
	v_pk_mul_f32 v[50:51], v[50:51], v[186:187] op_sel_hi:[1,0]
	v_pk_mul_f32 v[48:49], v[48:49], v[186:187] op_sel_hi:[1,0]
	v_add_f32_e32 v76, v224, v76
	v_pk_mul_f32 v[14:15], v[14:15], v[186:187] op_sel_hi:[1,0]
; #define MFMA(a, b, c) __builtin_amdgcn_mfma_f32_32x32x16_bf16((a), (b), (c), 0, 0, 0)
; DI unsigned pack2(float a, float b) { const f32x2 v = {a, b}; return __builtin_bit_cast(unsigned, __builtin_convertvector(v, bf16v2)); }
; DI void phase_xattn(const Params& p, char* lds) {
;     ...
;       const float mnew = fmaxf(mrun, mx), alpha = __builtin_amdgcn_exp2f(mrun - mnew);
;       mrun = mnew;
;       float ps = 0.f;
; #pragma unroll
;       for (int r = 0; r < 16; ++r) { const float e = __builtin_amdgcn_exp2f(S[r] - mnew); S[r] = e; ps += e; }
;       lrun = lrun * alpha + ps;
;       bf16x8 Pf[2];
; #pragma unroll
;       for (int ks = 0; ks < 2; ++ks) {
;         union { bf16x8 v; unsigned u[4]; } cv;
;         for (int j2 = 0; j2 < 4; ++j2) cv.u[j2] = pack2(S[8 * ks + 2 * j2], S[8 * ks + 2 * j2 + 1]);
;         Pf[ks] = cv.v;
;       }
; #pragma unroll
;       for (int dt = 0; dt < 4; ++dt) {
; #pragma unroll
;         for (int r = 0; r < 16; ++r) O[dt][r] *= alpha;
; #pragma unroll
;         for (int ks = 0; ks < 2; ++ks) O[dt] = MFMA(ldfrag(vl + dt * 32 * 40 + 16 * ks), Pf[ks], O[dt]);
;       }
	v_pk_mul_f32 v[12:13], v[12:13], v[186:187] op_sel_hi:[1,0]
	v_mfma_f32_32x32x16_bf16 v[48:63], v[188:191], v[64:67], v[48:63]
	v_mul_f32_e64 v10, v10, v186
	v_mul_f32_e64 v11, v11, v186
	v_mul_f32_e64 v8, v8, v186
	v_mul_f32_e64 v9, v9, v186
	v_mul_f32_e64 v6, v6, v186
	v_mul_f32_e64 v7, v7, v186
	v_pk_mul_f32 v[4:5], v[4:5], v[186:187] op_sel_hi:[1,0]
	v_pk_mul_f32 v[2:3], v[2:3], v[186:187] op_sel_hi:[1,0]
	v_pk_mul_f32 v[0:1], v[0:1], v[186:187] op_sel_hi:[1,0]
	v_pk_mul_f32 v[46:47], v[46:47], v[186:187] op_sel_hi:[1,0]
	v_pk_mul_f32 v[44:45], v[44:45], v[186:187] op_sel_hi:[1,0]
	v_pk_mul_f32 v[42:43], v[42:43], v[186:187] op_sel_hi:[1,0]
	v_pk_mul_f32 v[40:41], v[40:41], v[186:187] op_sel_hi:[1,0]
	v_pk_mul_f32 v[38:39], v[38:39], v[186:187] op_sel_hi:[1,0]
	v_pk_mul_f32 v[36:37], v[36:37], v[186:187] op_sel_hi:[1,0]
	v_pk_mul_f32 v[34:35], v[34:35], v[186:187] op_sel_hi:[1,0]
	v_pk_mul_f32 v[32:33], v[32:33], v[186:187] op_sel_hi:[1,0]
	v_exp_f32_e32 v188, v77
	v_exp_f32_e32 v189, v78
	v_exp_f32_e32 v190, v79
	v_pk_mul_f32 v[30:31], v[30:31], v[186:187] op_sel_hi:[1,0]
	v_add_f32_e32 v191, v225, v76
	v_pk_mul_f32 v[28:29], v[28:29], v[186:187] op_sel_hi:[1,0]
	v_pk_mul_f32 v[26:27], v[26:27], v[186:187] op_sel_hi:[1,0]
	v_pk_mul_f32 v[24:25], v[24:25], v[186:187] op_sel_hi:[1,0]
	v_pk_mul_f32 v[22:23], v[22:23], v[186:187] op_sel_hi:[1,0]
	v_pk_mul_f32 v[20:21], v[20:21], v[186:187] op_sel_hi:[1,0]
	v_pk_mul_f32 v[18:19], v[18:19], v[186:187] op_sel_hi:[1,0]
	v_pk_mul_f32 v[16:17], v[16:17], v[186:187] op_sel_hi:[1,0]
	ds_read_b128 v[76:79], v200 offset:41504
	s_waitcnt lgkmcnt(5)
	v_mfma_f32_32x32x16_bf16 v[0:15], v[192:195], v[64:67], v[0:15]
	v_cvt_pk_bf16_f32 v68, v223, v224
	v_cvt_pk_bf16_f32 v69, v225, v226
	v_cvt_pk_bf16_f32 v70, v227, v188
	v_cvt_pk_bf16_f32 v71, v189, v190
	s_waitcnt lgkmcnt(3)
	v_mfma_f32_32x32x16_bf16 v[32:47], v[208:211], v[64:67], v[32:47]
	s_waitcnt lgkmcnt(1)
	v_mfma_f32_32x32x16_bf16 v[16:31], v[72:75], v[64:67], v[16:31]
	v_add_f32_e32 v64, v226, v191
	v_add_f32_e32 v64, v227, v64
	v_add_f32_e32 v64, v188, v64
	v_add_f32_e32 v64, v189, v64
	v_add_f32_e32 v64, v190, v64
	v_fmac_f32_e32 v64, v185, v186
	v_mfma_f32_32x32x16_bf16 v[48:63], v[196:199], v[68:71], v[48:63]
	v_mfma_f32_32x32x16_bf16 v[0:15], v[204:207], v[68:71], v[0:15]
	v_mfma_f32_32x32x16_bf16 v[32:47], v[212:215], v[68:71], v[32:47]
	s_waitcnt lgkmcnt(0)
	v_mfma_f32_32x32x16_bf16 v[16:31], v[76:79], v[68:71], v[16:31]
	s_cbranch_scc1 .LBB0_907
; DI unsigned pack2(float a, float b) { const f32x2 v = {a, b}; return __builtin_bit_cast(unsigned, __builtin_convertvector(v, bf16v2)); }
; DI f32x16 zero16() { f32x16 z; for (int i = 0; i < 16; ++i) z[i] = 0.f; return z; }
; DI void phase_xattn(const Params& p, char* lds) {
;     ...
;       if (kt == 7) {
;         const float inv = __builtin_amdgcn_rcpf(lrun + __shfl_xor(lrun, 32));
; #pragma unroll
;         for (int dt = 0; dt < 4; ++dt) {
; #pragma unroll
;           for (int g = 0; g < 4; ++g) {
;             uint2 o; o.x = pack2(O[dt][4 * g] * inv, O[dt][4 * g + 1] * inv); o.y = pack2(O[dt][4 * g + 2] * inv, O[dt][4 * g + 3] * inv);
;             *(uint2*)(XO + (q0 + l31) * 1024 + h * 256 + dh * 128 + dt * 32 + 8 * g + 4 * hh) = o;
;           }
;           O[dt] = zero16();
;         }
;         mrun = -INFINITY; lrun = 0.f;
;       }
	ds_bpermute_b32 v65, v184, v64
	s_and_b32 s6, s15, 0x80
	s_lshl_b32 s6, s6, 1
	v_lshl_add_u64 v[66:67], v[180:181], 0, s[6:7]
	v_mov_b32_e32 v187, 0xff800000
	s_waitcnt lgkmcnt(0)
	v_add_f32_e32 v64, v64, v65
	v_rcp_f32_e32 v64, v64
	s_nop 0
	v_pk_mul_f32 v[0:1], v[0:1], v[64:65] op_sel_hi:[1,0]
	v_pk_mul_f32 v[2:3], v[2:3], v[64:65] op_sel_hi:[1,0]
	v_cvt_pk_bf16_f32 v0, v0, v1
	v_cvt_pk_bf16_f32 v1, v2, v3
	global_store_dwordx2 v[66:67], v[0:1], off offset:64
	v_pk_mul_f32 v[0:1], v[4:5], v[64:65] op_sel_hi:[1,0]
	v_pk_mul_f32 v[2:3], v[6:7], v[64:65] op_sel_hi:[1,0]
	v_cvt_pk_bf16_f32 v0, v0, v1
	v_cvt_pk_bf16_f32 v1, v2, v3
	global_store_dwordx2 v[66:67], v[0:1], off offset:80
	v_pk_mul_f32 v[0:1], v[8:9], v[64:65] op_sel_hi:[1,0]
	v_pk_mul_f32 v[2:3], v[10:11], v[64:65] op_sel_hi:[1,0]
	v_cvt_pk_bf16_f32 v0, v0, v1
	v_cvt_pk_bf16_f32 v1, v2, v3
	global_store_dwordx2 v[66:67], v[0:1], off offset:96
	v_pk_mul_f32 v[0:1], v[12:13], v[64:65] op_sel_hi:[1,0]
	v_pk_mul_f32 v[2:3], v[14:15], v[64:65] op_sel_hi:[1,0]
	v_cvt_pk_bf16_f32 v0, v0, v1
	v_cvt_pk_bf16_f32 v1, v2, v3
	global_store_dwordx2 v[66:67], v[0:1], off offset:112
	v_pk_mul_f32 v[0:1], v[32:33], v[64:65] op_sel_hi:[1,0]
	v_pk_mul_f32 v[2:3], v[34:35], v[64:65] op_sel_hi:[1,0]
	v_cvt_pk_bf16_f32 v0, v0, v1
	v_cvt_pk_bf16_f32 v1, v2, v3
	global_store_dwordx2 v[66:67], v[0:1], off offset:128
	v_pk_mul_f32 v[0:1], v[36:37], v[64:65] op_sel_hi:[1,0]
	v_pk_mul_f32 v[2:3], v[38:39], v[64:65] op_sel_hi:[1,0]
	v_cvt_pk_bf16_f32 v0, v0, v1
	v_cvt_pk_bf16_f32 v1, v2, v3
	global_store_dwordx2 v[66:67], v[0:1], off offset:144
	v_pk_mul_f32 v[0:1], v[40:41], v[64:65] op_sel_hi:[1,0]
	v_pk_mul_f32 v[2:3], v[42:43], v[64:65] op_sel_hi:[1,0]
	v_cvt_pk_bf16_f32 v0, v0, v1
	v_cvt_pk_bf16_f32 v1, v2, v3
	global_store_dwordx2 v[66:67], v[0:1], off offset:160
	v_pk_mul_f32 v[0:1], v[44:45], v[64:65] op_sel_hi:[1,0]
	v_pk_mul_f32 v[2:3], v[46:47], v[64:65] op_sel_hi:[1,0]
	v_cvt_pk_bf16_f32 v0, v0, v1
	v_cvt_pk_bf16_f32 v1, v2, v3
	v_pk_mul_f32 v[48:49], v[48:49], v[64:65] op_sel_hi:[1,0]
	v_pk_mul_f32 v[50:51], v[50:51], v[64:65] op_sel_hi:[1,0]
	global_store_dwordx2 v[66:67], v[0:1], off offset:176
	v_pk_mul_f32 v[0:1], v[16:17], v[64:65] op_sel_hi:[1,0]
	v_pk_mul_f32 v[2:3], v[18:19], v[64:65] op_sel_hi:[1,0]
	v_cvt_pk_bf16_f32 v48, v48, v49
	v_cvt_pk_bf16_f32 v49, v50, v51
	v_cvt_pk_bf16_f32 v0, v0, v1
	v_cvt_pk_bf16_f32 v1, v2, v3
	v_pk_mul_f32 v[52:53], v[52:53], v[64:65] op_sel_hi:[1,0]
	global_store_dwordx2 v[66:67], v[48:49], off
	v_pk_mul_f32 v[48:49], v[54:55], v[64:65] op_sel_hi:[1,0]
	global_store_dwordx2 v[66:67], v[0:1], off offset:192
	v_pk_mul_f32 v[0:1], v[20:21], v[64:65] op_sel_hi:[1,0]
	v_pk_mul_f32 v[2:3], v[22:23], v[64:65] op_sel_hi:[1,0]
	v_cvt_pk_bf16_f32 v50, v52, v53
	v_cvt_pk_bf16_f32 v51, v48, v49
	v_cvt_pk_bf16_f32 v0, v0, v1
	v_cvt_pk_bf16_f32 v1, v2, v3
	global_store_dwordx2 v[66:67], v[50:51], off offset:16
	v_pk_mul_f32 v[48:49], v[56:57], v[64:65] op_sel_hi:[1,0]
	v_pk_mul_f32 v[50:51], v[58:59], v[64:65] op_sel_hi:[1,0]
	global_store_dwordx2 v[66:67], v[0:1], off offset:208
	v_pk_mul_f32 v[0:1], v[24:25], v[64:65] op_sel_hi:[1,0]
	v_pk_mul_f32 v[2:3], v[26:27], v[64:65] op_sel_hi:[1,0]
	v_cvt_pk_bf16_f32 v48, v48, v49
	v_cvt_pk_bf16_f32 v49, v50, v51
	v_cvt_pk_bf16_f32 v0, v0, v1
	v_cvt_pk_bf16_f32 v1, v2, v3
	global_store_dwordx2 v[66:67], v[48:49], off offset:32
	v_pk_mul_f32 v[48:49], v[60:61], v[64:65] op_sel_hi:[1,0]
	v_pk_mul_f32 v[50:51], v[62:63], v[64:65] op_sel_hi:[1,0]
	global_store_dwordx2 v[66:67], v[0:1], off offset:224
	v_pk_mul_f32 v[0:1], v[28:29], v[64:65] op_sel_hi:[1,0]
	v_pk_mul_f32 v[2:3], v[30:31], v[64:65] op_sel_hi:[1,0]
	v_cvt_pk_bf16_f32 v48, v48, v49
	v_cvt_pk_bf16_f32 v49, v50, v51
	v_cvt_pk_bf16_f32 v0, v0, v1
	v_cvt_pk_bf16_f32 v1, v2, v3
	v_mov_b32_e32 v64, 0
	global_store_dwordx2 v[66:67], v[48:49], off offset:48
	global_store_dwordx2 v[66:67], v[0:1], off offset:240
	v_mov_b32_e32 v0, 0
	v_mov_b32_e32 v1, v64
	v_mov_b32_e32 v2, v64
	v_mov_b32_e32 v3, v64
	v_mov_b32_e32 v4, v64
	v_mov_b32_e32 v5, v64
	v_mov_b32_e32 v6, v64
	v_mov_b32_e32 v7, v64
	v_mov_b32_e32 v8, v64
	v_mov_b32_e32 v9, v64
	v_mov_b32_e32 v10, v64
	v_mov_b32_e32 v11, v64
	v_mov_b32_e32 v12, v64
	v_mov_b32_e32 v13, v64
	v_mov_b32_e32 v14, v64
	v_mov_b32_e32 v15, v64
	v_mov_b32_e32 v48, 0
	v_mov_b32_e32 v49, v64
	v_mov_b32_e32 v50, v64
	v_mov_b32_e32 v51, v64
	v_mov_b32_e32 v52, v64
	v_mov_b32_e32 v53, v64
	v_mov_b32_e32 v54, v64
	v_mov_b32_e32 v55, v64
	v_mov_b32_e32 v56, v64
	v_mov_b32_e32 v57, v64
	v_mov_b32_e32 v58, v64
	v_mov_b32_e32 v59, v64
	v_mov_b32_e32 v60, v64
	v_mov_b32_e32 v61, v64
	v_mov_b32_e32 v62, v64
	v_mov_b32_e32 v63, v64
	v_mov_b32_e32 v32, 0
	v_mov_b32_e32 v33, v64
	v_mov_b32_e32 v34, v64
	v_mov_b32_e32 v35, v64
	v_mov_b32_e32 v36, v64
	v_mov_b32_e32 v37, v64
	v_mov_b32_e32 v38, v64
	v_mov_b32_e32 v39, v64
	v_mov_b32_e32 v40, v64
	v_mov_b32_e32 v41, v64
	v_mov_b32_e32 v42, v64
	v_mov_b32_e32 v43, v64
	v_mov_b32_e32 v44, v64
	v_mov_b32_e32 v45, v64
	v_mov_b32_e32 v46, v64
	v_mov_b32_e32 v47, v64
	v_mov_b32_e32 v16, 0
	v_mov_b32_e32 v17, v64
	v_mov_b32_e32 v18, v64
	v_mov_b32_e32 v19, v64
	v_mov_b32_e32 v20, v64
	v_mov_b32_e32 v21, v64
	v_mov_b32_e32 v22, v64
	v_mov_b32_e32 v23, v64
	v_mov_b32_e32 v24, v64
	v_mov_b32_e32 v25, v64
	v_mov_b32_e32 v26, v64
	v_mov_b32_e32 v27, v64
	v_mov_b32_e32 v28, v64
	v_mov_b32_e32 v29, v64
	v_mov_b32_e32 v30, v64
	v_mov_b32_e32 v31, v64
